# item-dealing phases (sc_conv x2, hyena dwconv, untranspose, attn prep): priority 1 for the waves that own one item more
# speedup vs baseline: 1.0005x; 1.0005x over previous
.LBB0_353:
	s_cmp_gt_i32 s60, 3
	s_cselect_b64 s[4:5], -1, 0
	s_cmp_eq_u32 s61, 3
	s_cselect_b64 s[6:7], -1, 0
	s_or_b64 s[4:5], s[4:5], s[6:7]
	s_and_b64 vcc, exec, s[4:5]
	s_cbranch_vccnz .LBB0_420
	v_readlane_b32 s100, v255, 6
	s_cmp_gt_u32 s100, 1
	s_cbranch_scc1 .Lwprio_sc0
	s_setprio 1
.Lwprio_sc0:
	s_mul_hi_i32 s7, s2, 0x2200
	s_mul_i32 s6, s2, 0x2200
	s_ashr_i32 s57, s56, 31
	s_or_b64 s[4:5], s[6:7], s[56:57]
	s_mov_b32 s4, 0
	v_and_b32_e32 v1, 63, v0
	s_cmp_lg_u64 s[4:5], 0
	s_cbranch_scc0 .LBB0_380
	s_ashr_i32 s4, s57, 31
	s_add_u32 s8, s56, s4
	s_mov_b32 s5, s4
	s_addc_u32 s9, s57, s4
	s_xor_b64 s[10:11], s[8:9], s[4:5]
	v_cvt_f32_u32_e32 v2, s10
	v_cvt_f32_u32_e32 v3, s11
	s_sub_u32 s3, 0, s10
	s_subb_u32 s14, 0, s11
	v_fmamk_f32 v2, v3, 0x4f800000, v2
	v_rcp_f32_e32 v2, v2
	s_nop 0
	v_mul_f32_e32 v2, 0x5f7ffffc, v2
	v_mul_f32_e32 v3, 0x2f800000, v2
	v_trunc_f32_e32 v3, v3
	v_fmamk_f32 v2, v3, 0xcf800000, v2
	v_cvt_u32_f32_e32 v3, v3
	v_cvt_u32_f32_e32 v2, v2
	v_readfirstlane_b32 s15, v3
	v_readfirstlane_b32 s12, v2
	s_mul_i32 s13, s3, s15
	s_mul_hi_u32 s17, s3, s12
	s_mul_i32 s16, s14, s12
	s_add_i32 s13, s17, s13
	s_add_i32 s13, s13, s16
	s_mul_i32 s18, s3, s12
	s_mul_i32 s17, s12, s13
	s_mul_hi_u32 s19, s12, s18
	s_mul_hi_u32 s16, s12, s13
	s_add_u32 s17, s19, s17
	s_addc_u32 s16, 0, s16
	s_mul_hi_u32 s20, s15, s18
	s_mul_i32 s18, s15, s18
	s_add_u32 s17, s17, s18
	s_mul_hi_u32 s19, s15, s13
	s_addc_u32 s16, s16, s20
	s_addc_u32 s17, s19, 0
	s_mul_i32 s13, s15, s13
	s_add_u32 s13, s16, s13
	s_addc_u32 s16, 0, s17
	s_add_u32 s17, s12, s13
	s_cselect_b64 s[12:13], -1, 0
	s_cmp_lg_u64 s[12:13], 0
	s_addc_u32 s15, s15, s16
	s_mul_i32 s12, s3, s15
	s_mul_hi_u32 s13, s3, s17
	s_add_i32 s12, s13, s12
	s_mul_i32 s14, s14, s17
	s_add_i32 s12, s12, s14
	s_mul_i32 s3, s3, s17
	s_mul_hi_u32 s14, s15, s3
	s_mul_i32 s16, s15, s3
	s_mul_i32 s19, s17, s12
	s_mul_hi_u32 s3, s17, s3
	s_mul_hi_u32 s18, s17, s12
	s_add_u32 s3, s3, s19
	s_addc_u32 s18, 0, s18
	s_add_u32 s3, s3, s16
	s_mul_hi_u32 s13, s15, s12
	s_addc_u32 s3, s18, s14
	s_addc_u32 s13, s13, 0
	s_mul_i32 s12, s15, s12
	s_add_u32 s3, s3, s12
	s_addc_u32 s14, 0, s13
	s_add_u32 s3, s17, s3
	s_cselect_b64 s[12:13], -1, 0
	s_cmp_lg_u64 s[12:13], 0
	s_addc_u32 s16, s15, s14
	s_ashr_i32 s12, s7, 31
	s_add_u32 s14, s6, s12
	s_mov_b32 s13, s12
	s_addc_u32 s15, s7, s12
	s_xor_b64 s[14:15], s[14:15], s[12:13]
	s_mul_i32 s17, s14, s16
	s_mul_hi_u32 s18, s14, s3
	s_mul_hi_u32 s7, s14, s16
	s_add_u32 s17, s18, s17
	s_addc_u32 s7, 0, s7
	s_mul_hi_u32 s19, s15, s3
	s_mul_i32 s3, s15, s3
	s_add_u32 s3, s17, s3
	s_mul_hi_u32 s18, s15, s16
	s_addc_u32 s3, s7, s19
	s_addc_u32 s7, s18, 0
	s_mul_i32 s16, s15, s16
	s_add_u32 s3, s3, s16
	s_addc_u32 s7, 0, s7
	s_mul_i32 s16, s10, s7
	s_mul_hi_u32 s17, s10, s3
	s_add_i32 s16, s17, s16
	s_mul_i32 s17, s11, s3
	s_add_i32 s20, s16, s17
	s_sub_i32 s18, s15, s20
	s_mul_i32 s16, s10, s3
	s_sub_u32 s14, s14, s16
	s_cselect_b64 s[16:17], -1, 0
	s_cmp_lg_u64 s[16:17], 0
	s_subb_u32 s21, s18, s11
	s_sub_u32 s22, s14, s10
	s_cselect_b64 s[18:19], -1, 0
	s_cmp_lg_u64 s[18:19], 0
	s_subb_u32 s18, s21, 0
	s_cmp_ge_u32 s18, s11
	s_cselect_b32 s19, -1, 0
	s_cmp_ge_u32 s22, s10
	s_cselect_b32 s21, -1, 0
	s_cmp_eq_u32 s18, s11
	s_cselect_b32 s18, s21, s19
	s_add_u32 s19, s3, 1
	s_addc_u32 s21, s7, 0
	s_add_u32 s22, s3, 2
	s_addc_u32 s23, s7, 0
	s_cmp_lg_u32 s18, 0
	s_cselect_b32 s18, s22, s19
	s_cselect_b32 s19, s23, s21
	s_cmp_lg_u64 s[16:17], 0
	s_subb_u32 s15, s15, s20
	s_cmp_ge_u32 s15, s11
	s_cselect_b32 s16, -1, 0
	s_cmp_ge_u32 s14, s10
	s_cselect_b32 s10, -1, 0
	s_cmp_eq_u32 s15, s11
	s_cselect_b32 s10, s10, s16
	s_cmp_lg_u32 s10, 0
	s_cselect_b32 s11, s19, s7
	s_cselect_b32 s10, s18, s3
	s_xor_b64 s[4:5], s[12:13], s[4:5]
	s_xor_b64 s[10:11], s[10:11], s[4:5]
	s_sub_u32 s4, s10, s4
	v_cvt_f32_u32_e32 v2, s56
	s_cbranch_execnz .LBB0_357

.LBB0_420:
	s_setprio 0
	s_cmp_gt_i32 s60, 6
	s_cselect_b64 s[4:5], -1, 0
	s_cmp_lt_i32 s61, 7
	s_cselect_b64 s[6:7], -1, 0
	s_or_b64 s[4:5], s[4:5], s[6:7]
	s_and_b64 vcc, exec, s[4:5]
	s_cbranch_vccnz .LBB0_506
	s_cmpk_lg_i32 s56, 0x100
	s_cselect_b64 s[4:5], -1, 0
	s_cmp_lt_u32 s2, 32
	s_cselect_b64 s[6:7], -1, 0
	s_or_b64 s[4:5], s[6:7], s[4:5]
	s_and_b64 vcc, exec, s[4:5]
	s_cbranch_vccnz .LBB0_439
	v_mov_b32_e32 v3, v0
	v_and_b32_e32 v2, 63, v0
	s_cmpk_gt_i32 s2, 0x45f
	s_cbranch_scc1 .LBB0_439
	v_add_u32_e32 v14, 0x400, v3
	v_ashrrev_i32_e32 v14, 6, v14
	v_ashrrev_i32_e32 v15, 31, v14
	v_lshlrev_b64 v[18:19], 14, v[14:15]
	v_add_u32_e32 v14, 0x600, v3
	v_ashrrev_i32_e32 v14, 6, v14
	v_ashrrev_i32_e32 v15, 31, v14
	v_lshlrev_b64 v[20:21], 14, v[14:15]
	v_add_u32_e32 v14, 0x800, v3
	v_ashrrev_i32_e32 v14, 6, v14
	v_ashrrev_i32_e32 v15, 31, v14
	s_load_dwordx2 s[4:5], s[0:1], 0x80
	v_lshlrev_b64 v[22:23], 14, v[14:15]
	v_add_u32_e32 v14, 0xa00, v3
	v_ashrrev_i32_e32 v14, 6, v14
	v_ashrrev_i32_e32 v15, 31, v14
	v_lshlrev_b32_e32 v1, 4, v3
	v_lshlrev_b64 v[24:25], 14, v[14:15]
	v_add_u32_e32 v14, 0xc00, v3
	v_lshlrev_b32_e32 v10, 2, v3
	v_and_b32_e32 v4, 0x3f0, v1
	v_mov_b32_e32 v5, 0
	v_ashrrev_i32_e32 v14, 6, v14
	s_waitcnt lgkmcnt(0)
	v_lshl_add_u64 v[4:5], s[4:5], 0, v[4:5]
	v_and_b32_e32 v6, 60, v10
	s_movk_i32 s4, 0x104
	v_ashrrev_i32_e32 v15, 31, v14
	v_mad_u32_u24 v16, v6, s4, 0
	v_readlane_b32 s8, v255, 5
	v_ashrrev_i32_e32 v6, 2, v2
	v_lshlrev_b64 v[26:27], 14, v[14:15]
	v_add_u32_e32 v14, 0xe00, v3
	s_bfe_u32 s5, s8, 0x20006
	v_and_b32_e32 v6, -4, v6
	v_ashrrev_i32_e32 v14, 6, v14
	v_lshl_add_u32 v53, s5, 4, v6
	v_ashrrev_i32_e32 v6, 6, v3
	v_add_u32_e32 v33, 0x200, v3
	v_ashrrev_i32_e32 v15, 31, v14
	v_ashrrev_i32_e32 v3, 4, v3
	v_and_b32_e32 v30, 15, v2
	v_and_b32_e32 v17, 0x3ffffff0, v2
	s_lshl_b32 s6, s5, 6
	v_lshlrev_b64 v[28:29], 14, v[14:15]
	v_lshl_add_u32 v54, v3, 2, v16
	v_ashrrev_i32_e32 v3, 4, v33
	v_or_b32_e32 v14, 15, v2
	s_add_i32 s6, s6, 0
	v_lshlrev_b32_e32 v31, 2, v30
	v_ashrrev_i32_e32 v8, 6, v33
	v_lshl_add_u32 v55, v3, 2, v16
	v_mul_lo_u32 v3, v17, s4
	v_mul_lo_u32 v33, v14, s4
	s_and_b32 s4, s2, 15
	s_mov_b32 s7, 0
	v_add_u32_e32 v32, s6, v31
	s_lshl_b32 s6, s4, 10
	v_lshl_add_u64 v[4:5], v[4:5], 0, s[6:7]
	s_lshl_b32 s6, s2, 8
	s_sub_i32 s3, s2, 32
	s_and_b32 s7, s6, 0x300
	s_cmp_lt_u32 s4, 8
	v_lshlrev_b32_e32 v2, 10, v2
	s_cselect_b64 s[4:5], -1, 0
	s_lshr_b32 s8, s8, 8
	v_and_b32_e32 v2, 0xffffc000, v2
	v_lshl_add_u32 v2, s8, 9, v2
	v_ashrrev_i32_e32 v7, 31, v6
	v_ashrrev_i32_e32 v9, 31, v8
	s_lshl_b32 s9, s8, 7
	v_or_b32_e32 v2, v2, v31
	v_add_u32_e32 v1, 0, v1
	v_add_u32_e32 v12, 0x800, v10
	v_lshlrev_b64 v[6:7], 14, v[6:7]
	v_lshlrev_b64 v[8:9], 14, v[8:9]
	s_add_i32 s7, s7, s9
	v_add_u32_e32 v2, 0, v2
	v_add_u32_e32 v52, 0x4100, v1
	v_ashrrev_i32_e32 v11, 31, v10
	v_ashrrev_i32_e32 v13, 31, v12
	v_lshl_add_u64 v[14:15], v[4:5], 0, v[6:7]
	v_lshl_add_u64 v[16:17], v[4:5], 0, v[8:9]
	v_lshl_add_u64 v[18:19], v[4:5], 0, v[18:19]
	v_lshl_add_u64 v[20:21], v[4:5], 0, v[20:21]
	v_lshl_add_u64 v[22:23], v[4:5], 0, v[22:23]
	v_lshl_add_u64 v[24:25], v[4:5], 0, v[24:25]
	v_lshl_add_u64 v[26:27], v[4:5], 0, v[26:27]
	v_lshl_add_u64 v[28:29], v[4:5], 0, v[28:29]
	v_or_b32_e32 v56, s7, v30
	s_add_i32 s14, s6, 0xffffe000
	v_add_u32_e32 v57, 0x4100, v2
	s_mov_b64 s[8:9], 0
	s_mov_b32 s15, 0x200000
	v_add_u32_e32 v58, v32, v3
	v_add_u32_e32 v59, v32, v33
	s_movk_i32 s16, 0x1000
	s_mov_b32 s17, 0x37700000
	v_mov_b32_e32 v60, 0xc0447cbd
	s_branch .LBB0_425

.LBB0_1075:
	s_add_u32 s14, s52, 0x32700000
	s_addc_u32 s15, s53, 0
	s_cmp_gt_i32 s60, 15
	s_cselect_b64 s[4:5], -1, 0
	s_cmp_eq_u32 s61, 15
	s_cselect_b64 s[6:7], -1, 0
	s_or_b64 s[4:5], s[4:5], s[6:7]
	s_and_b64 vcc, exec, s[4:5]
	s_cbranch_vccnz .LBB0_1142
	v_readlane_b32 s100, v255, 6
	s_cmp_gt_u32 s100, 2
	s_cbranch_scc1 .Lwprio_dw
	s_setprio 1
.Lwprio_dw:
	s_mul_hi_i32 s5, s2, 0x3300
	s_mul_i32 s4, s2, 0x3300
	s_ashr_i32 s57, s56, 31
	s_or_b64 s[6:7], s[4:5], s[56:57]
	s_mov_b32 s6, 0
	v_and_b32_e32 v1, 63, v0
	s_cmp_lg_u64 s[6:7], 0
	s_cbranch_scc0 .LBB0_1102
	s_ashr_i32 s6, s57, 31
	s_add_u32 s8, s56, s6
	s_mov_b32 s7, s6
	s_addc_u32 s9, s57, s6
	s_xor_b64 s[10:11], s[8:9], s[6:7]
	s_waitcnt vmcnt(0)
	v_cvt_f32_u32_e32 v2, s10
	v_cvt_f32_u32_e32 v3, s11
	s_sub_u32 s3, 0, s10
	s_subb_u32 s16, 0, s11
	v_fmamk_f32 v2, v3, 0x4f800000, v2
	v_rcp_f32_e32 v2, v2
	s_nop 0
	v_mul_f32_e32 v2, 0x5f7ffffc, v2
	v_mul_f32_e32 v3, 0x2f800000, v2
	v_trunc_f32_e32 v3, v3
	v_fmamk_f32 v2, v3, 0xcf800000, v2
	v_cvt_u32_f32_e32 v3, v3
	v_cvt_u32_f32_e32 v2, v2
	v_readfirstlane_b32 s17, v3
	v_readfirstlane_b32 s12, v2
	s_mul_i32 s13, s3, s17
	s_mul_hi_u32 s19, s3, s12
	s_mul_i32 s18, s16, s12
	s_add_i32 s13, s19, s13
	s_add_i32 s13, s13, s18
	s_mul_i32 s20, s3, s12
	s_mul_i32 s19, s12, s13
	s_mul_hi_u32 s21, s12, s20
	s_mul_hi_u32 s18, s12, s13
	s_add_u32 s19, s21, s19
	s_addc_u32 s18, 0, s18
	s_mul_hi_u32 s22, s17, s20
	s_mul_i32 s20, s17, s20
	s_add_u32 s19, s19, s20
	s_mul_hi_u32 s21, s17, s13
	s_addc_u32 s18, s18, s22
	s_addc_u32 s19, s21, 0
	s_mul_i32 s13, s17, s13
	s_add_u32 s13, s18, s13
	s_addc_u32 s18, 0, s19
	s_add_u32 s19, s12, s13
	s_cselect_b64 s[12:13], -1, 0
	s_cmp_lg_u64 s[12:13], 0
	s_addc_u32 s17, s17, s18
	s_mul_i32 s12, s3, s17
	s_mul_hi_u32 s13, s3, s19
	s_add_i32 s12, s13, s12
	s_mul_i32 s16, s16, s19
	s_add_i32 s12, s12, s16
	s_mul_i32 s3, s3, s19
	s_mul_hi_u32 s16, s17, s3
	s_mul_i32 s18, s17, s3
	s_mul_i32 s21, s19, s12
	s_mul_hi_u32 s3, s19, s3
	s_mul_hi_u32 s20, s19, s12
	s_add_u32 s3, s3, s21
	s_addc_u32 s20, 0, s20
	s_add_u32 s3, s3, s18
	s_mul_hi_u32 s13, s17, s12
	s_addc_u32 s3, s20, s16
	s_addc_u32 s13, s13, 0
	s_mul_i32 s12, s17, s12
	s_add_u32 s3, s3, s12
	s_addc_u32 s16, 0, s13
	s_add_u32 s3, s19, s3
	s_cselect_b64 s[12:13], -1, 0
	s_cmp_lg_u64 s[12:13], 0
	s_addc_u32 s18, s17, s16
	s_ashr_i32 s12, s5, 31
	s_add_u32 s16, s4, s12
	s_mov_b32 s13, s12
	s_addc_u32 s17, s5, s12
	s_xor_b64 s[16:17], s[16:17], s[12:13]
	s_mul_i32 s19, s16, s18
	s_mul_hi_u32 s20, s16, s3
	s_mul_hi_u32 s5, s16, s18
	s_add_u32 s19, s20, s19
	s_addc_u32 s5, 0, s5
	s_mul_hi_u32 s21, s17, s3
	s_mul_i32 s3, s17, s3
	s_add_u32 s3, s19, s3
	s_mul_hi_u32 s20, s17, s18
	s_addc_u32 s3, s5, s21
	s_addc_u32 s5, s20, 0
	s_mul_i32 s18, s17, s18
	s_add_u32 s3, s3, s18
	s_addc_u32 s5, 0, s5
	s_mul_i32 s18, s10, s5
	s_mul_hi_u32 s19, s10, s3
	s_add_i32 s18, s19, s18
	s_mul_i32 s19, s11, s3
	s_add_i32 s22, s18, s19
	s_sub_i32 s20, s17, s22
	s_mul_i32 s18, s10, s3
	s_sub_u32 s16, s16, s18
	s_cselect_b64 s[18:19], -1, 0
	s_cmp_lg_u64 s[18:19], 0
	s_subb_u32 s23, s20, s11
	s_sub_u32 s24, s16, s10
	s_cselect_b64 s[20:21], -1, 0
	s_cmp_lg_u64 s[20:21], 0
	s_subb_u32 s20, s23, 0
	s_cmp_ge_u32 s20, s11
	s_cselect_b32 s21, -1, 0
	s_cmp_ge_u32 s24, s10
	s_cselect_b32 s23, -1, 0
	s_cmp_eq_u32 s20, s11
	s_cselect_b32 s20, s23, s21
	s_add_u32 s21, s3, 1
	s_addc_u32 s23, s5, 0
	s_add_u32 s24, s3, 2
	s_addc_u32 s25, s5, 0
	s_cmp_lg_u32 s20, 0
	s_cselect_b32 s20, s24, s21
	s_cselect_b32 s21, s25, s23
	s_cmp_lg_u64 s[18:19], 0
	s_subb_u32 s17, s17, s22
	s_cmp_ge_u32 s17, s11
	s_cselect_b32 s18, -1, 0
	s_cmp_ge_u32 s16, s10
	s_cselect_b32 s10, -1, 0
	s_cmp_eq_u32 s17, s11
	s_cselect_b32 s10, s10, s18
	s_cmp_lg_u32 s10, 0
	s_cselect_b32 s11, s21, s5
	s_cselect_b32 s10, s20, s3
	s_xor_b64 s[6:7], s[12:13], s[6:7]
	s_xor_b64 s[10:11], s[10:11], s[6:7]
	s_sub_u32 s6, s10, s6
	v_cvt_f32_u32_e32 v2, s56
	s_cbranch_execnz .LBB0_1079

.LBB0_1142:
	s_setprio 0
	s_cmp_gt_i32 s60, 16
	s_cselect_b64 s[4:5], -1, 0
	s_cmp_lt_i32 s61, 17
	s_cselect_b64 s[6:7], -1, 0
	s_or_b64 s[4:5], s[4:5], s[6:7]
	s_and_b64 vcc, exec, s[4:5]
	s_cbranch_vccnz .LBB0_1240
	v_mov_b32_e32 v26, v0
	s_movk_i32 s3, 0x800
	v_and_b32_e32 v101, 63, v0
	v_cmp_gt_i32_e64 s[4:5], s3, v26
	v_ashrrev_i32_e32 v27, 31, v26
	s_and_saveexec_b64 s[6:7], s[4:5]
	s_cbranch_execz .LBB0_1146
	s_waitcnt vmcnt(0)
	v_lshl_add_u32 v2, v26, 3, 0
	v_add_u32_e32 v4, 0x21000, v2
	v_lshl_add_u64 v[2:3], v[26:27], 3, s[52:53]
	s_mov_b64 s[8:9], 0x310000
	v_add_u32_e32 v1, 0xfffffe00, v26
	v_lshl_add_u64 v[2:3], v[2:3], 0, s[8:9]
	s_mov_b64 s[8:9], 0
	s_mov_b64 s[10:11], 0x1000
	s_movk_i32 s3, 0x5ff

.LBB0_1240:
	s_cmp_gt_i32 s60, 17
	s_cselect_b64 s[4:5], -1, 0
	s_cmp_lt_i32 s61, 18
	s_cselect_b64 s[6:7], -1, 0
	s_or_b64 s[4:5], s[4:5], s[6:7]
	s_and_b64 vcc, exec, s[4:5]
	s_cbranch_vccnz .LBB0_1314
	v_readlane_b32 s100, v255, 6
	s_cmp_gt_u32 s100, 1
	s_cbranch_scc1 .Lwprio_ut
	s_setprio 1
.Lwprio_ut:
	s_mul_hi_i32 s7, s2, 0x2200
	s_mul_i32 s6, s2, 0x2200
	s_ashr_i32 s57, s56, 31
	s_or_b64 s[4:5], s[6:7], s[56:57]
	s_mov_b32 s4, 0
	s_waitcnt vmcnt(0)
	v_and_b32_e32 v2, 63, v0
	s_cmp_lg_u64 s[4:5], 0
	s_cbranch_scc0 .LBB0_1251
	s_ashr_i32 s4, s57, 31
	s_add_u32 s8, s56, s4
	s_mov_b32 s5, s4
	s_addc_u32 s9, s57, s4
	s_xor_b64 s[10:11], s[8:9], s[4:5]
	v_cvt_f32_u32_e32 v1, s10
	v_cvt_f32_u32_e32 v3, s11
	s_sub_u32 s3, 0, s10
	s_subb_u32 s14, 0, s11
	v_fmamk_f32 v1, v3, 0x4f800000, v1
	v_rcp_f32_e32 v1, v1
	s_nop 0
	v_mul_f32_e32 v1, 0x5f7ffffc, v1
	v_mul_f32_e32 v3, 0x2f800000, v1
	v_trunc_f32_e32 v3, v3
	v_fmamk_f32 v1, v3, 0xcf800000, v1
	v_cvt_u32_f32_e32 v3, v3
	v_cvt_u32_f32_e32 v1, v1
	v_readfirstlane_b32 s15, v3
	v_readfirstlane_b32 s12, v1
	s_mul_i32 s13, s3, s15
	s_mul_hi_u32 s17, s3, s12
	s_mul_i32 s16, s14, s12
	s_add_i32 s13, s17, s13
	s_add_i32 s13, s13, s16
	s_mul_i32 s18, s3, s12
	s_mul_i32 s17, s12, s13
	s_mul_hi_u32 s19, s12, s18
	s_mul_hi_u32 s16, s12, s13
	s_add_u32 s17, s19, s17
	s_addc_u32 s16, 0, s16
	s_mul_hi_u32 s20, s15, s18
	s_mul_i32 s18, s15, s18
	s_add_u32 s17, s17, s18
	s_mul_hi_u32 s19, s15, s13
	s_addc_u32 s16, s16, s20
	s_addc_u32 s17, s19, 0
	s_mul_i32 s13, s15, s13
	s_add_u32 s13, s16, s13
	s_addc_u32 s16, 0, s17
	s_add_u32 s17, s12, s13
	s_cselect_b64 s[12:13], -1, 0
	s_cmp_lg_u64 s[12:13], 0
	s_addc_u32 s15, s15, s16
	s_mul_i32 s12, s3, s15
	s_mul_hi_u32 s13, s3, s17
	s_add_i32 s12, s13, s12
	s_mul_i32 s14, s14, s17
	s_add_i32 s12, s12, s14
	s_mul_i32 s3, s3, s17
	s_mul_hi_u32 s14, s15, s3
	s_mul_i32 s16, s15, s3
	s_mul_i32 s19, s17, s12
	s_mul_hi_u32 s3, s17, s3
	s_mul_hi_u32 s18, s17, s12
	s_add_u32 s3, s3, s19
	s_addc_u32 s18, 0, s18
	s_add_u32 s3, s3, s16
	s_mul_hi_u32 s13, s15, s12
	s_addc_u32 s3, s18, s14
	s_addc_u32 s13, s13, 0
	s_mul_i32 s12, s15, s12
	s_add_u32 s3, s3, s12
	s_addc_u32 s14, 0, s13
	s_add_u32 s3, s17, s3
	s_cselect_b64 s[12:13], -1, 0
	s_cmp_lg_u64 s[12:13], 0
	s_addc_u32 s16, s15, s14
	s_ashr_i32 s12, s7, 31
	s_add_u32 s14, s6, s12
	s_mov_b32 s13, s12
	s_addc_u32 s15, s7, s12
	s_xor_b64 s[14:15], s[14:15], s[12:13]
	s_mul_i32 s17, s14, s16
	s_mul_hi_u32 s18, s14, s3
	s_mul_hi_u32 s7, s14, s16
	s_add_u32 s17, s18, s17
	s_addc_u32 s7, 0, s7
	s_mul_hi_u32 s19, s15, s3
	s_mul_i32 s3, s15, s3
	s_add_u32 s3, s17, s3
	s_mul_hi_u32 s18, s15, s16
	s_addc_u32 s3, s7, s19
	s_addc_u32 s7, s18, 0
	s_mul_i32 s16, s15, s16
	s_add_u32 s3, s3, s16
	s_addc_u32 s7, 0, s7
	s_mul_i32 s16, s10, s7
	s_mul_hi_u32 s17, s10, s3
	s_add_i32 s16, s17, s16
	s_mul_i32 s17, s11, s3
	s_add_i32 s20, s16, s17
	s_sub_i32 s18, s15, s20
	s_mul_i32 s16, s10, s3
	s_sub_u32 s14, s14, s16
	s_cselect_b64 s[16:17], -1, 0
	s_cmp_lg_u64 s[16:17], 0
	s_subb_u32 s21, s18, s11
	s_sub_u32 s22, s14, s10
	s_cselect_b64 s[18:19], -1, 0
	s_cmp_lg_u64 s[18:19], 0
	s_subb_u32 s18, s21, 0
	s_cmp_ge_u32 s18, s11
	s_cselect_b32 s19, -1, 0
	s_cmp_ge_u32 s22, s10
	s_cselect_b32 s21, -1, 0
	s_cmp_eq_u32 s18, s11
	s_cselect_b32 s18, s21, s19
	s_add_u32 s19, s3, 1
	s_addc_u32 s21, s7, 0
	s_add_u32 s22, s3, 2
	s_addc_u32 s23, s7, 0
	s_cmp_lg_u32 s18, 0
	s_cselect_b32 s18, s22, s19
	s_cselect_b32 s19, s23, s21
	s_cmp_lg_u64 s[16:17], 0
	s_subb_u32 s15, s15, s20
	s_cmp_ge_u32 s15, s11
	s_cselect_b32 s16, -1, 0
	s_cmp_ge_u32 s14, s10
	s_cselect_b32 s10, -1, 0
	s_cmp_eq_u32 s15, s11
	s_cselect_b32 s10, s10, s16
	s_cmp_lg_u32 s10, 0
	s_cselect_b32 s11, s19, s7
	s_cselect_b32 s10, s18, s3
	s_xor_b64 s[4:5], s[12:13], s[4:5]
	s_xor_b64 s[10:11], s[10:11], s[4:5]
	s_sub_u32 s4, s10, s4
	v_cvt_f32_u32_e32 v1, s56
	s_cbranch_execnz .LBB0_1244

.LBB0_1314:
	s_setprio 0
	s_cmp_gt_i32 s60, 18
	s_cselect_b64 s[4:5], -1, 0
	s_cmp_lt_i32 s61, 19
	s_cselect_b64 s[6:7], -1, 0
	s_or_b64 s[4:5], s[4:5], s[6:7]
	s_and_b64 vcc, exec, s[4:5]
	s_cbranch_vccnz .LBB0_1390
	s_cmpk_lg_i32 s56, 0x100
	s_cselect_b64 s[4:5], -1, 0
	s_cmp_lt_i32 s2, 32
	s_cselect_b64 s[6:7], -1, 0
	s_or_b64 s[4:5], s[6:7], s[4:5]
	s_and_b64 vcc, exec, s[4:5]
	s_cbranch_vccnz .LBB0_1323
	s_add_i32 s3, s54, 0x9300
	s_cmp_gt_i32 s3, 0xbfff
	s_cbranch_scc1 .LBB0_1323
	v_readlane_b32 s4, v255, 6
	s_mulk_i32 s4, 0x2200
	s_add_i32 s11, s4, 0
	v_and_b32_e32 v1, 63, v0
	s_mov_b32 s5, 0
	s_mov_b32 s10, 0x10000
	s_add_i32 s11, s11, 0x10000
	s_lshl_b32 s12, s3, 1
	s_lshl_b32 s13, s3, 5
	s_mov_b32 s14, 0x7b00000
	s_waitcnt vmcnt(0)
	v_mov_b32_e32 v3, 0
	s_movk_i32 s15, 0x2000
	s_movk_i32 s16, 0x4000
	s_movk_i32 s17, 0x6000
	s_mov_b32 s18, 0x8000
	s_mov_b32 s19, 0xa000
	s_mov_b32 s20, 0xc000
	s_mov_b32 s21, 0xe000
	s_mov_b32 s22, 0x12000
	s_mov_b32 s23, 0x14000
	s_mov_b32 s24, 0x16000
	s_mov_b32 s25, 0x18000
	s_mov_b32 s26, 0x1a000
	s_mov_b32 s27, 0x1c000
	s_mov_b32 s28, 0x1e000
	s_mov_b32 s29, 0x20000
	s_mov_b32 s30, 0x22000
	s_mov_b32 s31, 0x24000
	s_mov_b32 s34, 0x26000
	s_mov_b32 s35, 0x28000
	s_mov_b32 s36, 0x2a000
	s_mov_b32 s37, 0x2c000
	s_mov_b32 s38, 0x2e000
	s_mov_b32 s39, 0x30000
	s_mov_b32 s41, 0x32000
	s_mov_b32 s42, 0x34000
	s_mov_b32 s43, 0x36000
	s_mov_b32 s45, 0x38000
	s_mov_b32 s46, 0x3a000
	s_mov_b32 s47, 0x3c000
	s_mov_b32 s49, 0x3e000
	s_movk_i32 s50, 0x84
	s_mov_b32 s51, 0x4b00000
	s_movk_i32 s57, 0xc8
	s_branch .LBB0_1319

.LBB0_1959:
	s_add_u32 s24, s52, 0x27800000
	s_addc_u32 s25, s53, 0
	s_cmp_gt_i32 s60, 27
	s_cselect_b64 s[4:5], -1, 0
	s_cmp_eq_u32 s61, 27
	s_cselect_b64 s[6:7], -1, 0
	s_or_b64 s[4:5], s[4:5], s[6:7]
	s_and_b64 vcc, exec, s[4:5]
	s_cbranch_vccnz .LBB0_2052
	v_readlane_b32 s100, v255, 6
	s_cmp_gt_u32 s100, 1
	s_cbranch_scc1 .Lwprio_ap
	s_setprio 1
.Lwprio_ap:
	s_load_dwordx4 s[12:15], s[0:1], 0xa8
	v_mov_b32_e32 v1, v0
	s_movk_i32 s3, 0x800
	s_waitcnt vmcnt(0) lgkmcnt(0)
	s_barrier
	s_nop 0
	v_cmp_gt_i32_e32 vcc, s3, v1
	s_and_saveexec_b64 s[10:11], vcc
	s_cbranch_execz .LBB0_1967
	v_and_b32_e32 v2, 31, v1
	v_cvt_f32_ubyte0_e32 v2, v2
	v_mul_f32_e32 v3, 0xbed49a78, v2
	s_mov_b32 s3, 0xc2fc0000
	v_mov_b32_e32 v4, 0x42800000
	v_cmp_gt_f32_e32 vcc, s3, v3
	v_lshl_add_u32 v6, v1, 3, 0
	s_mov_b64 s[16:17], 0
	v_cndmask_b32_e32 v3, 0, v4, vcc
	v_fmac_f32_e32 v3, 0xbed49a78, v2
	v_exp_f32_e32 v2, v3
	v_not_b32_e32 v4, 63
	v_cndmask_b32_e32 v3, 0, v4, vcc
	s_brev_b32 s3, 18
	v_ldexp_f32 v5, v2, v3
	s_mov_b32 s20, 0xfe5163ab
	v_mov_b32_e32 v3, 0
	s_mov_b32 s21, 0x3c439041
	s_mov_b32 s22, 0xdb629599
	s_mov_b32 s23, 0xf534ddc0
	s_mov_b32 s26, 0xfc2757d1
	s_mov_b32 s27, 0x4e441529
	s_mov_b32 s28, 0xa2f9836e
	s_mov_b32 s29, 0x3fc90fda
	s_mov_b32 s30, 0x3f22f983
	s_mov_b32 s31, 0xbfc90fda
	v_mov_b32_e32 v7, 0x3c0881c4
	v_mov_b32_e32 v8, 0xbab64f3b
	s_brev_b32 s34, 1
	s_movk_i32 s35, 0x1f8
	s_movk_i32 s36, 0x5ff
	v_not_b32_e32 v9, 31
	v_mov_b32_e32 v10, 0x7fc00000
	s_branch .LBB0_1963

.Laprio_skip:
.LBB0_2052:
	s_setprio 0
	s_cmp_gt_i32 s60, 28
	s_cselect_b64 s[4:5], -1, 0
	s_cmp_lt_i32 s61, 29
	s_cselect_b64 s[6:7], -1, 0
	s_or_b64 s[4:5], s[4:5], s[6:7]
	s_and_b64 vcc, exec, s[4:5]
	s_cbranch_vccnz .LBB0_2131
	s_waitcnt vmcnt(1)
	v_lshrrev_b32_e32 v11, 3, v0
	v_lshrrev_b32_e32 v8, 4, v0
	v_and_b32_e32 v11, 8, v11
	v_lshlrev_b32_e32 v9, 3, v0
	v_and_or_b32 v12, v8, 16, v11
	v_and_b32_e32 v10, 0x78, v9
	v_lshrrev_b32_e32 v13, 5, v0
	v_lshrrev_b32_e32 v12, 1, v12
	s_waitcnt vmcnt(0)
	v_bfe_u32 v14, v9, 5, 2
	v_bfe_u32 v15, v0, 4, 2
	v_or_b32_e32 v12, v12, v14
	v_and_or_b32 v13, v13, 4, v15
	v_lshlrev_b32_e32 v15, 1, v10
	v_lshlrev_b32_e32 v12, 9, v12
	v_lshlrev_b32_e32 v13, 6, v13
	v_and_b32_e32 v16, 48, v15
	v_or3_b32 v17, v12, v13, v16
	v_or_b32_e32 v12, 32, v8
	v_and_or_b32 v11, v12, 48, v11
	v_lshrrev_b32_e32 v11, 1, v11
	v_or_b32_e32 v11, v11, v14
	v_lshlrev_b32_e32 v11, 9, v11
	v_or3_b32 v11, v11, v13, v16
	v_lshlrev_b32_e32 v13, 4, v0
	v_lshlrev_b32_e32 v16, 1, v0
	v_bfe_u32 v3, v0, 5, 1
	v_and_b32_e32 v14, 0xc0, v13
	v_and_b32_e32 v16, 32, v16
	v_and_b32_e32 v9, 0x118, v9
	v_and_b32_e32 v2, 31, v0
	v_or3_b32 v9, v16, v14, v9
	v_lshlrev_b32_e32 v14, 8, v8
	v_lshlrev_b32_e32 v12, 8, v12
	v_and_b32_e32 v16, 0x70, v0
	v_lshlrev_b32_e32 v21, 4, v3
	s_lshl_b32 s3, s2, 7
	v_or_b32_e32 v8, v14, v10
	v_or_b32_e32 v10, v12, v10
	v_bitop3_b32 v19, v15, v14, v16 bitop3:0xde
	v_bitop3_b32 v15, v15, v12, v16 bitop3:0xde
	v_lshlrev_b32_e32 v12, 8, v2
	v_and_b32_e32 v13, 0x70, v13
	v_or_b32_e32 v14, 32, v21
	s_and_b32 s3, s3, 0x380
	s_lshr_b32 s4, s2, 3
	v_bitop3_b32 v23, v14, v12, v13 bitop3:0xde
	v_or_b32_e32 v14, 64, v21
	s_add_i32 s3, s3, s4
	v_bitop3_b32 v24, v14, v12, v13 bitop3:0xde
	v_or_b32_e32 v14, 0x60, v21
	v_bitop3_b32 v25, v14, v12, v13 bitop3:0xde
	v_or_b32_e32 v14, 0x80, v21
	s_cmpk_lg_i32 s56, 0x100
	v_lshrrev_b32_e32 v4, 1, v0
	v_bitop3_b32 v26, v14, v12, v13 bitop3:0xde
	v_or_b32_e32 v14, 0xa0, v21
	s_cselect_b64 s[26:27], -1, 0
	s_add_i32 s6, 0, 0x10000
	v_and_b32_e32 v5, 0x1c0, v0
	v_and_b32_e32 v7, 0xe0, v4
	v_bitop3_b32 v27, v14, v12, v13 bitop3:0xde
	v_or_b32_e32 v14, 0xc0, v21
	s_cmp_lg_u32 0, -1
	v_and_b32_e32 v1, 63, v0
	v_or_b32_e32 v4, v7, v2
	v_lshlrev_b32_e32 v6, 3, v3
	v_bitop3_b32 v28, v14, v12, v13 bitop3:0xde
	v_or_b32_e32 v14, 0xe0, v21
	v_lshlrev_b32_e32 v180, 13, v3
	v_lshl_add_u32 v3, v5, 2, s6
	s_cselect_b32 s6, 0, 0
	v_mul_u32_u24_e32 v4, 0x600, v4
	v_mov_b32_e32 v179, 0
	v_bitop3_b32 v22, v21, v12, v13 bitop3:0xde
	v_bitop3_b32 v13, v14, v12, v13 bitop3:0xde
	v_or_b32_e32 v12, 0x4000, v8
	v_or_b32_e32 v14, 0x6000, v8
	v_or_b32_e32 v16, 0x8000, v8
	v_or_b32_e32 v18, 0xa000, v8
	v_cmp_gt_u32_e64 s[4:5], 32, v1
	v_lshlrev_b32_e32 v20, 10, v7
	v_add_u32_e32 v1, s6, v9
	v_lshl_add_u32 v196, v2, 2, v3
	s_addk_i32 s6, 0x4000
	v_add_u32_e32 v198, v3, v21
	v_lshlrev_b32_e32 v3, 1, v8
	s_movk_i32 s29, 0x4000
	s_mov_b32 s36, 0x8000
	v_mov_b32_e32 v181, v179
	s_mov_b32 s8, 0
	v_add_u32_e32 v197, s6, v9
	v_or_b32_e32 v182, 0x24000, v3
	v_mov_b32_e32 v183, v179
	v_or_b32_e32 v184, 0x20000, v3
	v_mov_b32_e32 v185, v179
	v_or_b32_e32 v186, 0x18000, v3
	v_mov_b32_e32 v187, v179
	v_or_b32_e32 v188, 0x1c000, v3
	v_mov_b32_e32 v189, v179
	s_mov_b32 s37, 0x42b504f3
	s_mov_b32 s28, 0x3e0293ee
	s_mov_b32 s38, 0x27800000
	s_mov_b32 s39, 0x26700000
	v_lshlrev_b32_e32 v178, 1, v20
	v_lshlrev_b32_e32 v190, 1, v2
	s_movk_i32 s41, 0x7fff
	s_movk_i32 s42, 0x1000
	s_movk_i32 s43, 0x5000
	s_mov_b32 s45, 0x9000
	s_mov_b32 s46, 0xc000
	s_mov_b32 s47, 0xd000
	v_lshlrev_b32_e32 v192, 1, v4
	v_lshlrev_b32_e32 v194, 1, v6
	v_lshlrev_b32_e32 v199, 1, v8
	v_lshlrev_b32_e32 v200, 1, v10
	v_add_u32_e32 v201, 0, v17
	v_add_u32_e32 v202, 0, v11
	v_add_u32_e32 v203, 0, v19
	v_add_u32_e32 v204, 0, v15
	v_add_u32_e32 v205, 0, v22
	v_add_u32_e32 v206, 0, v23
	v_add_u32_e32 v207, 0, v24
	v_add_u32_e32 v208, 0, v25
	v_add_u32_e32 v209, 0, v26
	v_add_u32_e32 v210, 0, v27
	v_add_u32_e32 v211, 0, v28
	v_add_u32_e32 v212, 0, v13
	v_mov_b32_e32 v213, 0xf149f2ca
	v_lshlrev_b32_e32 v214, 1, v12
	v_lshlrev_b32_e32 v215, 1, v14
	v_lshlrev_b32_e32 v216, 1, v16
	v_lshlrev_b32_e32 v217, 1, v18
	s_mov_b32 s49, 0
	s_branch .LBB0_2056

.LBB0_2740:
	s_cmp_gt_i32 s60, 39
	s_cselect_b64 s[4:5], -1, 0
	s_cmp_eq_u32 s61, 39
	s_cselect_b64 s[6:7], -1, 0
	s_or_b64 s[4:5], s[4:5], s[6:7]
	s_and_b64 vcc, exec, s[4:5]
	v_and_b32_e32 v1, 63, v0
	s_cbranch_vccnz .LBB0_2807
	v_readlane_b32 s100, v255, 6
	s_cmp_gt_u32 s100, 1
	s_cbranch_scc1 .Lwprio_sc3
	s_setprio 1
.Lwprio_sc3:
	s_ashr_i32 s3, s2, 31
	s_lshl_b64 s[6:7], s[2:3], 13
	s_ashr_i32 s57, s56, 31
	s_or_b64 s[4:5], s[6:7], s[56:57]
	s_mov_b32 s4, 0
	s_waitcnt vmcnt(0)
	v_mov_b32_e32 v2, v1
	s_cmp_lg_u64 s[4:5], 0
	s_cbranch_scc0 .LBB0_2767
	s_ashr_i32 s4, s57, 31
	s_add_u32 s8, s56, s4
	s_mov_b32 s5, s4
	s_addc_u32 s9, s57, s4
	s_xor_b64 s[10:11], s[8:9], s[4:5]
	v_cvt_f32_u32_e32 v3, s10
	v_cvt_f32_u32_e32 v4, s11
	s_sub_u32 s14, 0, s10
	s_subb_u32 s15, 0, s11
	v_fmamk_f32 v3, v4, 0x4f800000, v3
	v_rcp_f32_e32 v3, v3
	s_nop 0
	v_mul_f32_e32 v3, 0x5f7ffffc, v3
	v_mul_f32_e32 v4, 0x2f800000, v3
	v_trunc_f32_e32 v4, v4
	v_fmamk_f32 v3, v4, 0xcf800000, v3
	v_cvt_u32_f32_e32 v4, v4
	v_cvt_u32_f32_e32 v3, v3
	v_readfirstlane_b32 s16, v4
	v_readfirstlane_b32 s12, v3
	s_mul_i32 s13, s14, s16
	s_mul_hi_u32 s18, s14, s12
	s_mul_i32 s17, s15, s12
	s_add_i32 s13, s18, s13
	s_add_i32 s13, s13, s17
	s_mul_i32 s19, s14, s12
	s_mul_i32 s18, s12, s13
	s_mul_hi_u32 s20, s12, s19
	s_mul_hi_u32 s17, s12, s13
	s_add_u32 s18, s20, s18
	s_addc_u32 s17, 0, s17
	s_mul_hi_u32 s21, s16, s19
	s_mul_i32 s19, s16, s19
	s_add_u32 s18, s18, s19
	s_mul_hi_u32 s20, s16, s13
	s_addc_u32 s17, s17, s21
	s_addc_u32 s18, s20, 0
	s_mul_i32 s13, s16, s13
	s_add_u32 s13, s17, s13
	s_addc_u32 s17, 0, s18
	s_add_u32 s18, s12, s13
	s_cselect_b64 s[12:13], -1, 0
	s_cmp_lg_u64 s[12:13], 0
	s_addc_u32 s16, s16, s17
	s_mul_i32 s12, s14, s16
	s_mul_hi_u32 s13, s14, s18
	s_add_i32 s12, s13, s12
	s_mul_i32 s15, s15, s18
	s_add_i32 s12, s12, s15
	s_mul_i32 s14, s14, s18
	s_mul_hi_u32 s15, s16, s14
	s_mul_i32 s17, s16, s14
	s_mul_i32 s20, s18, s12
	s_mul_hi_u32 s14, s18, s14
	s_mul_hi_u32 s19, s18, s12
	s_add_u32 s14, s14, s20
	s_addc_u32 s19, 0, s19
	s_add_u32 s14, s14, s17
	s_mul_hi_u32 s13, s16, s12
	s_addc_u32 s14, s19, s15
	s_addc_u32 s13, s13, 0
	s_mul_i32 s12, s16, s12
	s_add_u32 s12, s14, s12
	s_addc_u32 s14, 0, s13
	s_add_u32 s17, s18, s12
	s_cselect_b64 s[12:13], -1, 0
	s_cmp_lg_u64 s[12:13], 0
	s_addc_u32 s16, s16, s14
	s_ashr_i32 s12, s7, 31
	s_add_u32 s14, s6, s12
	s_mov_b32 s13, s12
	s_addc_u32 s15, s7, s12
	s_xor_b64 s[14:15], s[14:15], s[12:13]
	s_mul_i32 s18, s14, s16
	s_mul_hi_u32 s19, s14, s17
	s_mul_hi_u32 s7, s14, s16
	s_add_u32 s18, s19, s18
	s_addc_u32 s7, 0, s7
	s_mul_hi_u32 s20, s15, s17
	s_mul_i32 s17, s15, s17
	s_add_u32 s17, s18, s17
	s_mul_hi_u32 s19, s15, s16
	s_addc_u32 s7, s7, s20
	s_addc_u32 s17, s19, 0
	s_mul_i32 s16, s15, s16
	s_add_u32 s7, s7, s16
	s_addc_u32 s20, 0, s17
	s_mul_i32 s16, s10, s20
	s_mul_hi_u32 s17, s10, s7
	s_add_i32 s16, s17, s16
	s_mul_i32 s17, s11, s7
	s_add_i32 s21, s16, s17
	s_sub_i32 s18, s15, s21
	s_mul_i32 s16, s10, s7
	s_sub_u32 s14, s14, s16
	s_cselect_b64 s[16:17], -1, 0
	s_cmp_lg_u64 s[16:17], 0
	s_subb_u32 s22, s18, s11
	s_sub_u32 s23, s14, s10
	s_cselect_b64 s[18:19], -1, 0
	s_cmp_lg_u64 s[18:19], 0
	s_subb_u32 s18, s22, 0
	s_cmp_ge_u32 s18, s11
	s_cselect_b32 s19, -1, 0
	s_cmp_ge_u32 s23, s10
	s_cselect_b32 s22, -1, 0
	s_cmp_eq_u32 s18, s11
	s_cselect_b32 s18, s22, s19
	s_add_u32 s19, s7, 1
	s_addc_u32 s22, s20, 0
	s_add_u32 s23, s7, 2
	s_addc_u32 s24, s20, 0
	s_cmp_lg_u32 s18, 0
	s_cselect_b32 s18, s23, s19
	s_cselect_b32 s19, s24, s22
	s_cmp_lg_u64 s[16:17], 0
	s_subb_u32 s15, s15, s21
	s_cmp_ge_u32 s15, s11
	s_cselect_b32 s16, -1, 0
	s_cmp_ge_u32 s14, s10
	s_cselect_b32 s10, -1, 0
	s_cmp_eq_u32 s15, s11
	s_cselect_b32 s10, s10, s16
	s_cmp_lg_u32 s10, 0
	s_cselect_b32 s11, s19, s20
	s_cselect_b32 s10, s18, s7
	s_xor_b64 s[4:5], s[12:13], s[4:5]
	s_xor_b64 s[10:11], s[10:11], s[4:5]
	s_sub_u32 s4, s10, s4
	v_cvt_f32_u32_e32 v3, s56
	s_cbranch_execnz .LBB0_2744

.LBB0_2807:
	s_setprio 0
	s_cmp_gt_i32 s60, 42
	s_cselect_b64 s[4:5], -1, 0
	s_cmp_lt_i32 s61, 43
	s_cselect_b64 s[6:7], -1, 0
	s_or_b64 s[4:5], s[4:5], s[6:7]
	s_and_b64 vcc, exec, s[4:5]
	s_cbranch_vccnz .LBB0_2883
	s_waitcnt vmcnt(0)
	v_mov_b32_e32 v2, v0
	s_cmpk_gt_i32 s2, 0x1ff
	v_readfirstlane_b32 s3, v2
	s_cbranch_scc1 .LBB0_2833
	s_ashr_i32 s14, s2, 31
	s_lshr_b32 s4, s14, 29
	s_add_i32 s7, s2, s4
	s_and_b32 s4, s7, -8
	s_sub_i32 s8, s2, s4
	s_cmp_gt_i32 s8, -1
	s_cbranch_scc0 .LBB0_2811
	s_lshl_b32 s6, s8, 6
	s_cbranch_execz .LBB0_2812
	s_branch .LBB0_2813
